# attention tile loop: per-half partial running row sums (one lane-half exchange after the loop instead of one per tile), canonicalising v_max x,x,x copies folded into the row-max ops, row-sum chain sta
# speedup vs baseline: 1.0203x; 1.0098x over previous
.LBB0_423:
	s_lshl_b32 s16, s19, 14
	s_add_i32 s4, s16, 16
	v_add_u32_e32 v96, s4, v185
	ds_read_b128 v[198:201], v96 offset:49152
	ds_read_b128 v[202:205], v96 offset:57344
	v_xor_b32_e32 v80, 0x80000000, v195
	v_mov_b32_e32 v81, v80
	v_mov_b64_e32 v[82:83], v[80:81]
	v_mov_b64_e32 v[84:85], v[80:81]
	v_mov_b64_e32 v[86:87], v[80:81]
	v_mov_b64_e32 v[88:89], v[80:81]
	v_mov_b64_e32 v[90:91], v[80:81]
	v_mov_b64_e32 v[92:93], v[80:81]
	v_mov_b64_e32 v[94:95], v[80:81]
	v_exp_f32_e32 v221, v64
	s_waitcnt lgkmcnt(1)
	v_mfma_f32_32x32x16_bf16 v[96:111], v[198:201], v[124:127], v[80:95]
	v_add_f32_e32 v64, v153, v152
	v_add_f32_e32 v64, v154, v64
	v_add_u32_e32 v197, s4, v189
	v_add_f32_e32 v64, v155, v64
	v_add_f32_e32 v64, v156, v64
	v_add_f32_e32 v64, v157, v64
	v_add_f32_e32 v64, v158, v64
	s_waitcnt lgkmcnt(0)
	v_mfma_f32_32x32x16_bf16 v[80:95], v[202:205], v[124:127], v[80:95]
	ds_read_b128 v[198:201], v197 offset:49152
	ds_read_b128 v[202:205], v197 offset:57344
	v_add_f32_e32 v64, v159, v64
	v_add_f32_e32 v64, v144, v64
	v_add_f32_e32 v64, v145, v64
	v_add_f32_e32 v64, v146, v64
	v_add_u32_e32 v197, s4, v192
	v_add_f32_e32 v64, v147, v64
	s_waitcnt lgkmcnt(1)
	v_mfma_f32_32x32x16_bf16 v[96:111], v[198:201], v[120:123], v[96:111]
	ds_read_b128 v[198:201], v197 offset:49152
	ds_read_b128 v[206:209], v197 offset:57344
	v_add_f32_e32 v64, v148, v64
	v_exp_f32_e32 v222, v65
	v_add_f32_e32 v64, v149, v64
	v_exp_f32_e32 v223, v66
	v_add_f32_e32 v64, v150, v64
	v_exp_f32_e32 v224, v67
	s_waitcnt lgkmcnt(2)
	v_mfma_f32_32x32x16_bf16 v[80:95], v[202:205], v[120:123], v[80:95]
	v_add_f32_e32 v64, v151, v64
	v_add_f32_e32 v64, v221, v64
	v_add_f32_e32 v64, v222, v64
	v_add_f32_e32 v64, v223, v64
	v_exp_f32_e32 v71, v71
	v_add_f32_e32 v64, v224, v64
	v_add_u32_e32 v197, s4, v194
	s_waitcnt lgkmcnt(1)
	v_mfma_f32_32x32x16_bf16 v[96:111], v[198:201], v[116:119], v[96:111]
	v_exp_f32_e32 v199, v68
	v_exp_f32_e32 v200, v69
	v_exp_f32_e32 v201, v70
	v_exp_f32_e32 v225, v72
	v_add_f32_e32 v64, v199, v64
	ds_read_b128 v[202:205], v197 offset:49152
	ds_read_b128 v[210:213], v197 offset:57344
	v_exp_f32_e32 v226, v73
	s_waitcnt lgkmcnt(2)
	v_mfma_f32_32x32x16_bf16 v[80:95], v[206:209], v[116:119], v[80:95]
	v_add_f32_e32 v64, v200, v64
	v_exp_f32_e32 v227, v74
	v_add_f32_e32 v64, v201, v64
	v_exp_f32_e32 v206, v75
	v_add_f32_e32 v64, v71, v64
	v_exp_f32_e32 v207, v76
	v_add_f32_e32 v64, v225, v64
	v_exp_f32_e32 v208, v77
	v_add_f32_e32 v64, v226, v64
	v_exp_f32_e32 v209, v78
	s_waitcnt lgkmcnt(1)
	v_mfma_f32_32x32x16_bf16 v[96:111], v[202:205], v[112:115], v[96:111]
	v_add_f32_e32 v64, v227, v64
	v_exp_f32_e32 v79, v79
	v_add_f32_e32 v64, v206, v64
	v_add_f32_e32 v64, v207, v64
	v_add_f32_e32 v64, v208, v64
	v_add_f32_e32 v64, v209, v64
	v_add_f32_e32 v197, v79, v64
	s_waitcnt lgkmcnt(0)
	v_mfma_f32_32x32x16_bf16 v[80:95], v[210:213], v[112:115], v[80:95]
	v_cvt_pk_bf16_f32 v64, v152, v153
	v_cvt_pk_bf16_f32 v65, v154, v155
	v_cvt_pk_bf16_f32 v66, v156, v157
	v_cvt_pk_bf16_f32 v67, v158, v159
	v_cvt_pk_bf16_f32 v72, v144, v145
	v_cvt_pk_bf16_f32 v73, v146, v147
	v_cvt_pk_bf16_f32 v74, v148, v149
	v_cvt_pk_bf16_f32 v75, v150, v151
	v_cvt_pk_bf16_f32 v68, v221, v222
	v_cvt_pk_bf16_f32 v69, v223, v224
	v_cvt_pk_bf16_f32 v70, v199, v200
	v_cvt_pk_bf16_f32 v71, v201, v71
	v_cvt_pk_bf16_f32 v76, v225, v226
	v_cvt_pk_bf16_f32 v77, v227, v206
	v_cvt_pk_bf16_f32 v78, v207, v208
	v_cvt_pk_bf16_f32 v79, v209, v79
	global_load_dwordx4 v[144:147], v244, s[98:99]
	global_load_dwordx4 v[148:151], v245, s[98:99]
	global_load_dwordx4 v[152:155], v242, s[98:99]
	global_load_dwordx4 v[156:159], v243, s[98:99]
	s_add_u32 s98, s98, 0x10000
	s_addc_u32 s99, s99, 0
	v_lshl_add_u32 v199, s18, 14, v181
	ds_read_b64_tr_b16 v[200:201], v199 offset:0
	ds_read_b64_tr_b16 v[202:203], v199 offset:0x100
	ds_read_b64_tr_b16 v[204:205], v199 offset:0x1000
	ds_read_b64_tr_b16 v[206:207], v199 offset:0x1100
	ds_read_b64_tr_b16 v[208:209], v199 offset:0x2000
	ds_read_b64_tr_b16 v[210:211], v199 offset:0x2100
	ds_read_b64_tr_b16 v[222:223], v199 offset:0x3000
	ds_read_b64_tr_b16 v[224:225], v199 offset:0x3100
	s_nop 0
	s_waitcnt lgkmcnt(6)
	v_mfma_f32_32x32x16_bf16 v[0:15], v[64:67], v[200:203], v[0:15]
	v_max_f32_e32 v200, v96, v97
	v_max3_f32 v200, v200, v98, v99
	v_max3_f32 v200, v200, v100, v101
	v_max3_f32 v200, v200, v102, v103
	v_max3_f32 v200, v200, v104, v105
	s_waitcnt lgkmcnt(4)
	v_mfma_f32_32x32x16_bf16 v[0:15], v[72:75], v[204:207], v[0:15]
	v_max3_f32 v200, v200, v106, v107
	v_max3_f32 v202, v200, v108, v109
	ds_read_b64_tr_b16 v[200:201], v199 offset:0x200
	v_max3_f32 v212, v202, v110, v111
	ds_read_b64_tr_b16 v[202:203], v199 offset:0x300
	ds_read_b64_tr_b16 v[204:205], v199 offset:0x1200
	ds_read_b64_tr_b16 v[206:207], v199 offset:0x1300
	s_waitcnt lgkmcnt(6)
	v_mfma_f32_32x32x16_bf16 v[0:15], v[68:71], v[208:211], v[0:15]
	ds_read_b64_tr_b16 v[208:209], v199 offset:0x2200
	ds_read_b64_tr_b16 v[210:211], v199 offset:0x2300
	ds_read_b64_tr_b16 v[226:227], v199 offset:0x3200
	ds_read_b64_tr_b16 v[228:229], v199 offset:0x3300
	s_waitcnt lgkmcnt(8)
	v_mfma_f32_32x32x16_bf16 v[0:15], v[76:79], v[222:225], v[0:15]
	s_waitcnt lgkmcnt(6)
	v_mfma_f32_32x32x16_bf16 v[48:63], v[64:67], v[200:203], v[48:63]
	v_max3_f32 v212, v212, v80, v81
	v_max3_f32 v200, v212, v82, v83
	ds_read_b64_tr_b16 v[202:203], v199 offset:0x400
	v_max3_f32 v200, v200, v84, v85
	v_max3_f32 v200, v200, v86, v87
	v_max3_f32 v200, v200, v88, v89
	v_max3_f32 v200, v200, v90, v91
	s_waitcnt lgkmcnt(5)
	v_mfma_f32_32x32x16_bf16 v[48:63], v[72:75], v[204:207], v[48:63]
	ds_read_b64_tr_b16 v[204:205], v199 offset:0x500
	ds_read_b64_tr_b16 v[206:207], v199 offset:0x1400
	v_max3_f32 v200, v200, v92, v93
	v_max3_f32 v200, v200, v94, v95
	v_mov_b32_e32 v201, v200
	s_nop 1
	v_permlane32_swap_b32_e32 v200, v201
	s_waitcnt lgkmcnt(5)
	v_mfma_f32_32x32x16_bf16 v[48:63], v[68:71], v[208:211], v[48:63]
	ds_read_b64_tr_b16 v[208:209], v199 offset:0x1500
	ds_read_b64_tr_b16 v[210:211], v199 offset:0x2400
	ds_read_b64_tr_b16 v[212:213], v199 offset:0x2500
	ds_read_b64_tr_b16 v[222:223], v199 offset:0x3400
	ds_read_b64_tr_b16 v[224:225], v199 offset:0x3500
	s_waitcnt lgkmcnt(8)
	v_mfma_f32_32x32x16_bf16 v[48:63], v[76:79], v[226:229], v[48:63]
	v_max_f32_e32 v200, v200, v201
	s_waitcnt lgkmcnt(6)
	v_mfma_f32_32x32x16_bf16 v[32:47], v[64:67], v[202:205], v[32:47]
	v_cmp_ge_f32_e32 vcc, s63, v200
	s_cmp_eq_u64 vcc, exec
	s_waitcnt lgkmcnt(4)
	v_mfma_f32_32x32x16_bf16 v[32:47], v[72:75], v[206:209], v[32:47]
	s_waitcnt lgkmcnt(2)
	v_mfma_f32_32x32x16_bf16 v[32:47], v[68:71], v[210:213], v[32:47]
	s_waitcnt lgkmcnt(0)
	v_mfma_f32_32x32x16_bf16 v[32:47], v[76:79], v[222:225], v[32:47]
	s_cbranch_scc0 .LBB0_438
	v_mov_b32_e32 v200, 1.0

.LBB0_429:
	v_exp_f32_e32 v199, v96
	v_exp_f32_e32 v221, v97
	v_exp_f32_e32 v226, v98
	v_exp_f32_e32 v227, v99
	v_exp_f32_e32 v228, v100
	v_exp_f32_e32 v229, v101
	v_exp_f32_e32 v230, v102
	v_exp_f32_e32 v231, v103
	v_exp_f32_e32 v232, v104
	v_exp_f32_e32 v233, v105
	v_exp_f32_e32 v234, v106
	v_exp_f32_e32 v235, v107
	v_exp_f32_e32 v236, v108
	v_exp_f32_e32 v237, v109
	v_exp_f32_e32 v238, v110
	v_exp_f32_e32 v239, v111
	s_waitcnt lgkmcnt(0)
	s_barrier
	v_add_u32_e32 v96, s17, v185
	ds_read_b128 v[202:205], v96 offset:49152
	ds_read_b128 v[206:209], v96 offset:57344
	v_xor_b32_e32 v64, 0x80000000, v195
	v_mov_b32_e32 v65, v64
	v_mov_b64_e32 v[66:67], v[64:65]
	v_mov_b64_e32 v[68:69], v[64:65]
	v_mov_b64_e32 v[70:71], v[64:65]
	v_mov_b64_e32 v[72:73], v[64:65]
	v_mov_b64_e32 v[74:75], v[64:65]
	v_mov_b64_e32 v[76:77], v[64:65]
	v_mov_b64_e32 v[78:79], v[64:65]
	v_add_u32_e32 v201, s17, v189
	v_exp_f32_e32 v80, v80
	s_waitcnt lgkmcnt(1)
	v_mfma_f32_32x32x16_bf16 v[96:111], v[202:205], v[124:127], v[64:79]
	v_exp_f32_e32 v81, v81
	v_exp_f32_e32 v82, v82
	v_exp_f32_e32 v83, v83
	v_exp_f32_e32 v84, v84
	v_exp_f32_e32 v85, v85
	v_exp_f32_e32 v86, v86
	v_exp_f32_e32 v87, v87
	s_waitcnt lgkmcnt(0)
	v_mfma_f32_32x32x16_bf16 v[64:79], v[206:209], v[124:127], v[64:79]
	ds_read_b128 v[202:205], v201 offset:49152
	ds_read_b128 v[206:209], v201 offset:57344
	v_add_u32_e32 v201, s17, v192
	v_exp_f32_e32 v240, v91
	v_exp_f32_e32 v241, v92
	v_cvt_pk_bf16_f32 v91, v230, v231
	v_cvt_pk_bf16_f32 v92, v232, v233
	s_waitcnt lgkmcnt(1)
	v_mfma_f32_32x32x16_bf16 v[96:111], v[202:205], v[120:123], v[96:111]
	ds_read_b128 v[202:205], v201 offset:49152
	ds_read_b128 v[210:213], v201 offset:57344
	v_add_u32_e32 v201, s17, v194
	s_waitcnt lgkmcnt(1)
	v_mfma_f32_32x32x16_bf16 v[96:111], v[202:205], v[116:119], v[96:111]
	v_exp_f32_e32 v203, v88
	v_add_f32_e32 v88, v221, v199
	v_add_f32_e32 v88, v226, v88
	v_add_f32_e32 v88, v227, v88
	v_add_f32_e32 v88, v228, v88
	v_add_f32_e32 v88, v229, v88
	v_add_f32_e32 v88, v230, v88
	v_add_f32_e32 v88, v231, v88
	v_add_f32_e32 v88, v232, v88
	v_add_f32_e32 v88, v233, v88
	v_mfma_f32_32x32x16_bf16 v[64:79], v[206:209], v[120:123], v[64:79]
	v_add_f32_e32 v88, v234, v88
	v_add_f32_e32 v88, v235, v88
	v_add_f32_e32 v88, v236, v88
	v_add_f32_e32 v88, v237, v88
	v_add_f32_e32 v88, v238, v88
	v_add_f32_e32 v88, v239, v88
	v_add_f32_e32 v88, v80, v88
	v_add_f32_e32 v88, v81, v88
	s_waitcnt lgkmcnt(0)
	v_mfma_f32_32x32x16_bf16 v[64:79], v[210:213], v[116:119], v[64:79]
	v_add_f32_e32 v88, v82, v88
	v_add_f32_e32 v88, v83, v88
	v_add_f32_e32 v88, v84, v88
	ds_read_b128 v[206:209], v201 offset:49152
	ds_read_b128 v[222:225], v201 offset:57344
	v_exp_f32_e32 v204, v89
	v_add_f32_e32 v88, v85, v88
	v_exp_f32_e32 v205, v90
	v_add_f32_e32 v88, v86, v88
	v_add_f32_e32 v88, v87, v88
	v_add_f32_e32 v88, v203, v88
	v_exp_f32_e32 v210, v93
	v_add_f32_e32 v88, v204, v88
	v_exp_f32_e32 v211, v94
	s_waitcnt lgkmcnt(1)
	v_mfma_f32_32x32x16_bf16 v[96:111], v[206:209], v[112:115], v[96:111]
	v_add_f32_e32 v88, v205, v88
	v_exp_f32_e32 v212, v95
	v_add_f32_e32 v88, v240, v88
	v_add_f32_e32 v88, v241, v88
	v_add_f32_e32 v88, v210, v88
	v_add_f32_e32 v88, v211, v88
	v_add_f32_e32 v201, v212, v88
	s_waitcnt lgkmcnt(0)
	v_mfma_f32_32x32x16_bf16 v[64:79], v[222:225], v[112:115], v[64:79]
	v_cvt_pk_bf16_f32 v88, v199, v221
	v_cvt_pk_bf16_f32 v89, v226, v227
	v_cvt_pk_bf16_f32 v90, v228, v229
	v_cvt_pk_bf16_f32 v93, v234, v235
	v_cvt_pk_bf16_f32 v94, v236, v237
	v_cvt_pk_bf16_f32 v95, v238, v239
	v_cvt_pk_bf16_f32 v80, v80, v81
	v_cvt_pk_bf16_f32 v81, v82, v83
	v_cvt_pk_bf16_f32 v82, v84, v85
	v_cvt_pk_bf16_f32 v83, v86, v87
	v_cvt_pk_bf16_f32 v84, v203, v204
	v_cvt_pk_bf16_f32 v85, v205, v240
	v_cvt_pk_bf16_f32 v86, v241, v210
	v_cvt_pk_bf16_f32 v87, v211, v212
	s_cmpk_gt_u32 s6, 0x7c
	s_cselect_b64 s[4:5], -1, 0
	s_and_b64 vcc, exec, s[4:5]
	s_cbranch_vccnz .Lattn_a0_lastw
	global_load_dwordx4 v[132:135], v244, s[98:99]
	global_load_dwordx4 v[128:131], v242, s[98:99]
	global_load_dwordx4 v[140:143], v245, s[98:99]
	global_load_dwordx4 v[136:139], v243, s[98:99]
	s_add_u32 s98, s98, 0x10000
	s_addc_u32 s99, s99, 0
.LBB0_431:
	v_add_u32_e32 v203, s16, v181
	ds_read_b64_tr_b16 v[204:205], v203 offset:0
	ds_read_b64_tr_b16 v[206:207], v203 offset:0x100
	ds_read_b64_tr_b16 v[208:209], v203 offset:0x1000
	ds_read_b64_tr_b16 v[210:211], v203 offset:0x1100
	ds_read_b64_tr_b16 v[222:223], v203 offset:0x2000
	ds_read_b64_tr_b16 v[224:225], v203 offset:0x2100
	ds_read_b64_tr_b16 v[226:227], v203 offset:0x3000
	ds_read_b64_tr_b16 v[228:229], v203 offset:0x3100
	s_waitcnt lgkmcnt(0)
	s_nop 0
	v_mfma_f32_32x32x16_bf16 v[0:15], v[88:91], v[204:207], v[0:15]
	v_max_f32_e32 v199, v96, v97
	ds_read_b64_tr_b16 v[204:205], v203 offset:0x200
	ds_read_b64_tr_b16 v[206:207], v203 offset:0x300
	v_max3_f32 v199, v199, v98, v99
	v_max3_f32 v199, v199, v100, v101
	v_mfma_f32_32x32x16_bf16 v[0:15], v[92:95], v[208:211], v[0:15]
	ds_read_b64_tr_b16 v[208:209], v203 offset:0x1200
	ds_read_b64_tr_b16 v[210:211], v203 offset:0x1300
	v_max3_f32 v199, v199, v102, v103
	v_max3_f32 v199, v199, v104, v105
	v_max3_f32 v199, v199, v106, v107
	v_max3_f32 v199, v199, v108, v109
	v_max3_f32 v199, v199, v110, v111
	v_mfma_f32_32x32x16_bf16 v[0:15], v[80:83], v[222:225], v[0:15]
	ds_read_b64_tr_b16 v[222:223], v203 offset:0x2200
	ds_read_b64_tr_b16 v[224:225], v203 offset:0x2300
	ds_read_b64_tr_b16 v[230:231], v203 offset:0x3200
	ds_read_b64_tr_b16 v[232:233], v203 offset:0x3300
	v_mfma_f32_32x32x16_bf16 v[0:15], v[84:87], v[226:229], v[0:15]
	s_waitcnt lgkmcnt(6)
	v_mfma_f32_32x32x16_bf16 v[48:63], v[88:91], v[204:207], v[48:63]
	v_max3_f32 v199, v199, v64, v65
	v_max3_f32 v199, v199, v66, v67
	ds_read_b64_tr_b16 v[206:207], v203 offset:0x400
	v_max3_f32 v199, v199, v68, v69
	v_max3_f32 v199, v199, v70, v71
	v_max3_f32 v199, v199, v72, v73
	v_max3_f32 v199, v199, v74, v75
	s_waitcnt lgkmcnt(5)
	v_mfma_f32_32x32x16_bf16 v[48:63], v[92:95], v[208:211], v[48:63]
	ds_read_b64_tr_b16 v[208:209], v203 offset:0x500
	ds_read_b64_tr_b16 v[210:211], v203 offset:0x1400
	ds_read_b64_tr_b16 v[212:213], v203 offset:0x1500
	v_max3_f32 v199, v199, v76, v77
	v_max3_f32 v199, v199, v78, v79
	v_mov_b32_e32 v204, v199
	s_nop 1
	v_permlane32_swap_b32_e32 v199, v204
	s_waitcnt lgkmcnt(6)
	v_mfma_f32_32x32x16_bf16 v[48:63], v[80:83], v[222:225], v[48:63]
	ds_read_b64_tr_b16 v[222:223], v203 offset:0x2400
	ds_read_b64_tr_b16 v[224:225], v203 offset:0x2500
	ds_read_b64_tr_b16 v[226:227], v203 offset:0x3400
	ds_read_b64_tr_b16 v[228:229], v203 offset:0x3500
	s_waitcnt lgkmcnt(8)
	v_mfma_f32_32x32x16_bf16 v[48:63], v[84:87], v[230:233], v[48:63]
	v_max_f32_e32 v204, v199, v204
	s_waitcnt lgkmcnt(6)
	v_mfma_f32_32x32x16_bf16 v[32:47], v[88:91], v[206:209], v[32:47]
	v_cmp_ge_f32_e32 vcc, s63, v204
	s_cmp_eq_u64 vcc, exec
	v_mov_b32_e32 v199, 1.0
	s_waitcnt lgkmcnt(4)
	v_mfma_f32_32x32x16_bf16 v[32:47], v[92:95], v[210:213], v[32:47]
	s_waitcnt lgkmcnt(2)
	v_mfma_f32_32x32x16_bf16 v[32:47], v[80:83], v[222:225], v[32:47]
	s_waitcnt lgkmcnt(0)
	v_mfma_f32_32x32x16_bf16 v[32:47], v[84:87], v[226:229], v[32:47]
	s_cbranch_scc0 .LBB0_439

.LBB0_436:
	v_exp_f32_e32 v152, v96
	v_exp_f32_e32 v153, v97
	v_exp_f32_e32 v154, v98
	v_exp_f32_e32 v155, v99
	v_exp_f32_e32 v156, v100
	v_exp_f32_e32 v157, v101
	v_exp_f32_e32 v158, v102
	v_exp_f32_e32 v159, v103
	v_exp_f32_e32 v144, v104
	v_exp_f32_e32 v145, v105
	v_exp_f32_e32 v146, v106
	v_exp_f32_e32 v147, v107
	v_exp_f32_e32 v148, v108
	v_exp_f32_e32 v149, v109
	v_exp_f32_e32 v150, v110
	v_exp_f32_e32 v151, v111
	v_fma_f32 v80, v196, v180, v197
	v_fma_f32 v180, v80, v200, v201
	s_add_i32 s6, s6, 2
	s_and_b64 vcc, exec, s[4:5]
	s_waitcnt lgkmcnt(0)
	s_barrier
	s_cbranch_vccnz .LBB0_440
	v_mov_b32_e32 v196, v199
	s_branch .LBB0_423

.LBB0_440:
	v_mov_b32_e32 v246, v180
	s_nop 1
	v_permlane32_swap_b32_e32 v180, v246
	v_add_f32_e32 v180, v180, v246
	v_or_b32_e32 v136, 0x2000, v190
	v_add_u32_e32 v90, s58, v185
	v_add3_u32 v96, v182, v136, s58
	ds_read_b128 v[128:131], v90
	ds_read_b128 v[132:135], v96
	v_xor_b32_e32 v80, 0x80000000, v195
	v_mov_b32_e32 v81, v80
	v_mov_b64_e32 v[82:83], v[80:81]
	v_mov_b64_e32 v[84:85], v[80:81]
	v_mov_b64_e32 v[86:87], v[80:81]
	v_mov_b64_e32 v[88:89], v[80:81]
	v_mov_b64_e32 v[90:91], v[80:81]
	v_mov_b64_e32 v[92:93], v[80:81]
	v_mov_b64_e32 v[94:95], v[80:81]
	v_exp_f32_e32 v137, v65
	v_exp_f32_e32 v138, v70
	s_waitcnt lgkmcnt(1)
	v_mfma_f32_32x32x16_bf16 v[96:111], v[128:131], v[124:127], v[80:95]
	v_add3_u32 v128, v187, v136, s58
	ds_read_b128 v[128:131], v128
	v_exp_f32_e32 v139, v71
	v_exp_f32_e32 v140, v72
	v_exp_f32_e32 v79, v79
	v_cvt_pk_bf16_f32 v65, v154, v155
	v_cvt_pk_bf16_f32 v70, v148, v149
	s_waitcnt lgkmcnt(1)
	v_mfma_f32_32x32x16_bf16 v[80:95], v[132:135], v[124:127], v[80:95]
	v_add_u32_e32 v124, s58, v189
	ds_read_b128 v[124:127], v124
	v_add3_u32 v132, v191, v136, s58
	v_cvt_pk_bf16_f32 v71, v150, v151
	s_waitcnt lgkmcnt(0)
	v_mfma_f32_32x32x16_bf16 v[96:111], v[124:127], v[120:123], v[96:111]
	v_add_u32_e32 v124, s58, v192
	ds_read_b128 v[124:127], v124
	v_mfma_f32_32x32x16_bf16 v[80:95], v[128:131], v[120:123], v[80:95]
	ds_read_b128 v[120:123], v132
	v_add3_u32 v132, v193, v136, s58
	v_exp_f32_e32 v136, v64
	v_add_f32_e32 v64, 0, v152
	v_add_f32_e32 v64, v153, v64
	v_add_f32_e32 v64, v154, v64
	v_add_f32_e32 v64, v155, v64
	v_add_f32_e32 v64, v156, v64
	v_add_f32_e32 v64, v157, v64
	v_add_f32_e32 v64, v158, v64
	v_add_f32_e32 v64, v159, v64
	v_add_f32_e32 v64, v144, v64
	v_add_f32_e32 v64, v145, v64
	v_add_f32_e32 v64, v146, v64
	v_add_f32_e32 v64, v147, v64
	v_add_f32_e32 v64, v148, v64
	v_add_f32_e32 v64, v149, v64
	s_waitcnt lgkmcnt(1)
	v_mfma_f32_32x32x16_bf16 v[96:111], v[124:127], v[116:119], v[96:111]
	v_exp_f32_e32 v124, v66
	v_add_f32_e32 v64, v150, v64
	v_exp_f32_e32 v125, v67
	v_add_f32_e32 v64, v151, v64
	v_exp_f32_e32 v126, v68
	v_add_f32_e32 v64, v136, v64
	v_exp_f32_e32 v127, v69
	v_add_f32_e32 v64, v137, v64
	s_waitcnt lgkmcnt(0)
	v_mfma_f32_32x32x16_bf16 v[80:95], v[120:123], v[116:119], v[80:95]
	v_add_f32_e32 v64, v124, v64
	v_add_f32_e32 v64, v125, v64
	v_add_u32_e32 v128, s58, v194
	v_add_f32_e32 v64, v126, v64
	ds_read_b128 v[128:131], v128
	ds_read_b128 v[132:135], v132
	v_exp_f32_e32 v116, v73
	v_add_f32_e32 v64, v127, v64
	v_exp_f32_e32 v117, v74
	v_add_f32_e32 v64, v138, v64
	v_exp_f32_e32 v118, v75
	v_add_f32_e32 v64, v139, v64
	v_exp_f32_e32 v119, v76
	v_add_f32_e32 v64, v140, v64
	v_exp_f32_e32 v120, v77
	v_add_f32_e32 v64, v116, v64
	v_exp_f32_e32 v121, v78
	s_waitcnt lgkmcnt(1)
	v_mfma_f32_32x32x16_bf16 v[96:111], v[128:131], v[112:115], v[96:111]
	v_add_f32_e32 v64, v117, v64
	v_add_f32_e32 v64, v118, v64
	v_add_f32_e32 v64, v119, v64
	v_add_f32_e32 v64, v120, v64
	v_add_f32_e32 v64, v121, v64
	v_cvt_pk_bf16_f32 v66, v156, v157
	v_cvt_pk_bf16_f32 v67, v158, v159
	s_waitcnt lgkmcnt(0)
	v_mfma_f32_32x32x16_bf16 v[80:95], v[132:135], v[112:115], v[80:95]
	v_add_f32_e32 v112, v79, v64
	v_mov_b32_e32 v113, v112
	v_cvt_pk_bf16_f32 v64, v152, v153
	v_cvt_pk_bf16_f32 v68, v144, v145
	v_cvt_pk_bf16_f32 v69, v146, v147
	v_cvt_pk_bf16_f32 v72, v136, v137
	v_cvt_pk_bf16_f32 v73, v124, v125
	v_cvt_pk_bf16_f32 v74, v126, v127
	v_cvt_pk_bf16_f32 v75, v138, v139
	v_cvt_pk_bf16_f32 v76, v140, v116
	v_cvt_pk_bf16_f32 v77, v117, v118
	v_cvt_pk_bf16_f32 v78, v119, v120
	v_cvt_pk_bf16_f32 v79, v121, v79
	v_permlane32_swap_b32_e32 v112, v113
	ds_read_b64_tr_b16 v[114:115], v181 offset:0
	ds_read_b64_tr_b16 v[116:117], v181 offset:0x100
	ds_read_b64_tr_b16 v[118:119], v181 offset:0x1000
	ds_read_b64_tr_b16 v[120:121], v181 offset:0x1100
	ds_read_b64_tr_b16 v[122:123], v181 offset:0x2000
	ds_read_b64_tr_b16 v[124:125], v181 offset:0x2100
	ds_read_b64_tr_b16 v[126:127], v181 offset:0x3000
	ds_read_b64_tr_b16 v[128:129], v181 offset:0x3100
	s_waitcnt lgkmcnt(0)
	s_nop 0
	v_mfma_f32_32x32x16_bf16 v[0:15], v[64:67], v[114:117], v[0:15]
	v_max_f32_e32 v114, v97, v97
	v_max_f32_e32 v115, v96, v96
	v_max_f32_e32 v114, v115, v114
	v_max3_f32 v114, v114, v98, v99
	v_max3_f32 v114, v114, v100, v101
	v_max3_f32 v114, v114, v102, v103
	v_max3_f32 v114, v114, v104, v105
	v_mfma_f32_32x32x16_bf16 v[0:15], v[68:71], v[118:121], v[0:15]
	v_max3_f32 v114, v114, v106, v107
	v_max3_f32 v116, v114, v108, v109
	ds_read_b64_tr_b16 v[114:115], v181 offset:0x200
	v_max3_f32 v134, v116, v110, v111
	ds_read_b64_tr_b16 v[116:117], v181 offset:0x300
	ds_read_b64_tr_b16 v[118:119], v181 offset:0x1200
	ds_read_b64_tr_b16 v[120:121], v181 offset:0x1300
	v_mfma_f32_32x32x16_bf16 v[0:15], v[72:75], v[122:125], v[0:15]
	ds_read_b64_tr_b16 v[122:123], v181 offset:0x2200
	ds_read_b64_tr_b16 v[124:125], v181 offset:0x2300
	ds_read_b64_tr_b16 v[130:131], v181 offset:0x3200
	ds_read_b64_tr_b16 v[132:133], v181 offset:0x3300
	s_waitcnt lgkmcnt(0)
	v_mfma_f32_32x32x16_bf16 v[0:15], v[76:79], v[126:129], v[0:15]
	v_mfma_f32_32x32x16_bf16 v[48:63], v[64:67], v[114:117], v[48:63]
	v_max3_f32 v126, v134, v80, v81
	v_max3_f32 v114, v126, v82, v83
	ds_read_b64_tr_b16 v[116:117], v181 offset:0x400
	v_max3_f32 v114, v114, v84, v85
	v_max3_f32 v114, v114, v86, v87
	v_max3_f32 v114, v114, v88, v89
	v_max3_f32 v114, v114, v90, v91
	v_mfma_f32_32x32x16_bf16 v[48:63], v[68:71], v[118:121], v[48:63]
	ds_read_b64_tr_b16 v[118:119], v181 offset:0x500
	ds_read_b64_tr_b16 v[120:121], v181 offset:0x1400
	v_max3_f32 v114, v114, v92, v93
	v_max3_f32 v114, v114, v94, v95
	v_mov_b32_e32 v115, v114
	s_nop 1
	v_permlane32_swap_b32_e32 v114, v115
	v_mfma_f32_32x32x16_bf16 v[48:63], v[72:75], v[122:125], v[48:63]
	ds_read_b64_tr_b16 v[122:123], v181 offset:0x1500
	ds_read_b64_tr_b16 v[124:125], v181 offset:0x2400
	ds_read_b64_tr_b16 v[126:127], v181 offset:0x2500
	ds_read_b64_tr_b16 v[134:135], v181 offset:0x3400
	ds_read_b64_tr_b16 v[136:137], v181 offset:0x3500
	s_waitcnt lgkmcnt(0)
	v_max_f32_e32 v115, v115, v115
	v_mfma_f32_32x32x16_bf16 v[48:63], v[76:79], v[130:133], v[48:63]
	v_max_f32_e32 v114, v114, v114
	v_max_f32_e32 v115, v114, v115
	v_mfma_f32_32x32x16_bf16 v[32:47], v[64:67], v[116:119], v[32:47]
	v_cmp_ge_f32_e32 vcc, s63, v115
	s_cmp_eq_u64 vcc, exec
	v_mov_b32_e32 v114, 1.0
	v_mfma_f32_32x32x16_bf16 v[32:47], v[68:71], v[120:123], v[32:47]
	v_mfma_f32_32x32x16_bf16 v[32:47], v[72:75], v[124:127], v[32:47]
	v_mfma_f32_32x32x16_bf16 v[32:47], v[76:79], v[134:137], v[32:47]
	s_cbranch_scc0 .LBB0_451
